# grid barrier top level on one counter (leaders add, everyone polls TOP >= (gen+1)*nx); G4 stats-exchange acquire invalidate issued before its poll; write-through stores for the last tile of the layer-
# speedup vs baseline: 1.0403x; 1.0066x over previous
.LBB0_53:
	s_or_b64 exec, exec, s[8:9]
	v_cvt_f32_u32_e32 v6, v4
	s_waitcnt vmcnt(0)
	v_readfirstlane_b32 s6, v5
	v_sub_u32_e32 v5, 0, v4
	v_rcp_iflag_f32_e32 v6, v6
	v_add_u32_e32 v7, s6, v3
	v_mul_f32_e32 v6, 0x4f7ffffe, v6
	v_cvt_u32_f32_e32 v6, v6
	v_mul_lo_u32 v3, v5, v6
	v_mul_hi_u32 v3, v6, v3
	v_add_u32_e32 v3, v6, v3
	v_mul_hi_u32 v3, v7, v3
	v_mul_lo_u32 v5, v3, v4
	v_sub_u32_e32 v5, v7, v5
	v_add_u32_e32 v6, 1, v3
	v_cmp_ge_u32_e32 vcc, v5, v4
	s_nop 1
	v_cndmask_b32_e32 v3, v3, v6, vcc
	v_sub_u32_e32 v6, v5, v4
	v_cndmask_b32_e32 v5, v5, v6, vcc
	v_add_u32_e32 v6, 1, v3
	v_cmp_ge_u32_e32 vcc, v5, v4
	v_add_u32_e32 v5, 1, v7
	s_nop 0
	v_cndmask_b32_e32 v3, v3, v6, vcc
	v_mul_lo_u32 v6, v4, v3
	v_add_u32_e32 v4, v6, v4
	v_cmp_ne_u32_e32 vcc, v5, v4
	s_and_saveexec_b64 s[6:7], vcc
	s_xor_b64 s[6:7], exec, s[6:7]
	s_cbranch_execz .LBB0_67
	s_movk_i32 s8, 0xd00
	buffer_inv sc1
	s_mov_b32 s9, 0
	s_lshl_b64 s[8:9], s[8:9], 2
	s_add_u32 s10, s4, s8
	s_addc_u32 s11, s5, s9
	s_waitcnt lgkmcnt(0)
	v_mad_u32_u24 v3, v3, v2, v2
	v_mov_b32_e32 v2, 0
	global_load_dword v4, v2, s[10:11] sc1
	s_waitcnt vmcnt(0)
	v_cmp_gt_u32_e32 vcc, v3, v4
	s_and_saveexec_b64 s[8:9], vcc
	s_cbranch_execz .LBB0_66
	s_mov_b32 s12, 1
	s_mov_b64 s[18:19], 0
	s_branch .LBB0_57

.LBB0_59:
	global_load_dword v4, v2, s[10:11] sc1
	s_add_i32 s12, s12, 1
	s_mov_b64 s[26:27], -1
	s_waitcnt vmcnt(0)
	v_cmp_le_u32_e32 vcc, v3, v4
	s_orn2_b64 s[24:25], vcc, exec
	s_branch .LBB0_56

.LBB0_70:
	s_or_b64 exec, exec, s[8:9]
	v_cvt_f32_u32_e32 v5, v2
	s_waitcnt vmcnt(0)
	v_readfirstlane_b32 s6, v4
	s_add_u32 s8, s4, 0x3400
	s_addc_u32 s9, s5, 0
	v_rcp_iflag_f32_e32 v5, v5
	v_add_u32_e32 v3, s6, v3
	v_add_u32_e32 v6, 1, v3
	s_mov_b64 s[10:11], -1
	v_mul_f32_e32 v4, 0x4f7ffffe, v5
	v_cvt_u32_f32_e32 v4, v4
	v_sub_u32_e32 v5, 0, v2
	v_mul_lo_u32 v5, v5, v4
	v_mul_hi_u32 v5, v4, v5
	v_add_u32_e32 v4, v4, v5
	v_mul_hi_u32 v4, v3, v4
	v_mul_lo_u32 v5, v4, v2
	v_sub_u32_e32 v3, v3, v5
	v_add_u32_e32 v7, 1, v4
	v_cmp_ge_u32_e32 vcc, v3, v2
	v_sub_u32_e32 v5, v3, v2
	s_nop 0
	v_cndmask_b32_e32 v4, v4, v7, vcc
	v_cndmask_b32_e32 v3, v3, v5, vcc
	v_add_u32_e32 v5, 1, v4
	v_cmp_ge_u32_e32 vcc, v3, v2
	s_nop 1
	v_cndmask_b32_e32 v4, v4, v5, vcc
	v_mul_lo_u32 v3, v2, v4
	v_add_u32_e32 v2, v3, v2
	v_cmp_ne_u32_e32 vcc, v6, v2
	v_mov_b32_e32 v4, v2
	v_mov_b64_e32 v[2:3], s[8:9]
	s_and_saveexec_b64 s[6:7], vcc
	s_cbranch_execz .LBB0_82
	v_mov_b32_e32 v2, 0
	global_load_dword v3, v2, s[8:9] sc1
	s_mov_b64 s[20:21], 0
	s_waitcnt vmcnt(0)
	v_cmp_gt_u32_e32 vcc, v4, v3
	s_and_saveexec_b64 s[18:19], vcc
	s_cbranch_execz .LBB0_81
	s_add_u32 s10, s4, 0x200
	s_addc_u32 s11, s5, 0
	s_mov_b32 s12, 1
	s_branch .LBB0_74

.LBB0_76:
	global_load_dword v3, v2, s[8:9] sc1
	s_add_i32 s12, s12, 1
	s_mov_b64 s[26:27], -1
	s_waitcnt vmcnt(0)
	v_cmp_le_u32_e32 vcc, v4, v3
	s_orn2_b64 s[30:31], vcc, exec
	s_branch .LBB0_73

.LBB0_82:
	s_or_b64 exec, exec, s[6:7]
	s_and_saveexec_b64 s[6:7], s[10:11]
	s_cbranch_execz .LBB0_84
	v_mov_b32_e32 v4, 1
.LBB0_84:
	s_or_b64 exec, exec, s[6:7]
	s_mov_b64 s[6:7], exec
	v_mbcnt_lo_u32_b32 v2, s6, 0
	v_mbcnt_hi_u32_b32 v2, s7, v2
	s_mov_b32 s11, 0
	v_cmp_eq_u32_e32 vcc, 0, v2
	s_waitcnt vmcnt(0)
	s_and_saveexec_b64 s[8:9], vcc
	s_cbranch_execz .LBB0_86
	s_add_i32 s10, s3, 0x900
	s_lshl_b64 s[10:11], s[10:11], 2
	s_add_u32 s4, s4, s10
	s_addc_u32 s5, s5, s11
	s_bcnt1_i32_b64 s3, s[6:7]
	v_mov_b32_e32 v2, 0
	v_mov_b32_e32 v3, s3
	s_nop 0

.LBB0_230:
	s_or_b64 exec, exec, s[24:25]
	v_cvt_f32_u32_e32 v6, v4
	s_waitcnt vmcnt(0)
	v_readfirstlane_b32 s8, v5
	v_sub_u32_e32 v5, 0, v4
	v_rcp_iflag_f32_e32 v6, v6
	v_add_u32_e32 v7, s8, v3
	v_mul_f32_e32 v6, 0x4f7ffffe, v6
	v_cvt_u32_f32_e32 v6, v6
	v_mul_lo_u32 v3, v5, v6
	v_mul_hi_u32 v3, v6, v3
	v_add_u32_e32 v3, v6, v3
	v_mul_hi_u32 v3, v7, v3
	v_mul_lo_u32 v5, v3, v4
	v_sub_u32_e32 v5, v7, v5
	v_add_u32_e32 v6, 1, v3
	v_cmp_ge_u32_e32 vcc, v5, v4
	s_nop 1
	v_cndmask_b32_e32 v3, v3, v6, vcc
	v_sub_u32_e32 v6, v5, v4
	v_cndmask_b32_e32 v5, v5, v6, vcc
	v_add_u32_e32 v6, 1, v3
	v_cmp_ge_u32_e32 vcc, v5, v4
	v_add_u32_e32 v5, 1, v7
	s_nop 0
	v_cndmask_b32_e32 v3, v3, v6, vcc
	v_mul_lo_u32 v6, v4, v3
	v_add_u32_e32 v4, v6, v4
	v_cmp_ne_u32_e32 vcc, v5, v4
	s_and_saveexec_b64 s[8:9], vcc
	s_xor_b64 s[8:9], exec, s[8:9]
	s_cbranch_execz .LBB0_244
	s_movk_i32 s14, 0xd00
	buffer_inv sc1
	s_mov_b32 s15, 0
	s_lshl_b64 s[14:15], s[14:15], 2
	s_add_u32 s26, s6, s14
	s_addc_u32 s27, s7, s15
	s_waitcnt lgkmcnt(0)
	v_mad_u32_u24 v3, v3, v2, v2
	v_mov_b32_e32 v2, 0
	global_load_dword v4, v2, s[26:27] sc1
	s_waitcnt vmcnt(0)
	v_cmp_gt_u32_e32 vcc, v3, v4
	s_and_saveexec_b64 s[24:25], vcc
	s_cbranch_execz .LBB0_243
	s_mov_b32 s13, 1
	s_mov_b64 s[28:29], 0
	s_branch .LBB0_234

.LBB0_236:
	global_load_dword v4, v2, s[26:27] sc1
	s_add_i32 s13, s13, 1
	s_mov_b64 s[38:39], -1
	s_waitcnt vmcnt(0)
	v_cmp_le_u32_e32 vcc, v3, v4
	s_orn2_b64 s[36:37], vcc, exec
	s_branch .LBB0_233

.LBB0_247:
	s_or_b64 exec, exec, s[24:25]
	v_cvt_f32_u32_e32 v5, v2
	s_waitcnt vmcnt(0)
	v_readfirstlane_b32 s8, v4
	s_add_u32 s24, s6, 0x3400
	s_addc_u32 s25, s7, 0
	v_rcp_iflag_f32_e32 v5, v5
	v_add_u32_e32 v3, s8, v3
	v_add_u32_e32 v6, 1, v3
	s_mov_b64 s[26:27], -1
	v_mul_f32_e32 v4, 0x4f7ffffe, v5
	v_cvt_u32_f32_e32 v4, v4
	v_sub_u32_e32 v5, 0, v2
	v_mul_lo_u32 v5, v5, v4
	v_mul_hi_u32 v5, v4, v5
	v_add_u32_e32 v4, v4, v5
	v_mul_hi_u32 v4, v3, v4
	v_mul_lo_u32 v5, v4, v2
	v_sub_u32_e32 v3, v3, v5
	v_add_u32_e32 v7, 1, v4
	v_cmp_ge_u32_e32 vcc, v3, v2
	v_sub_u32_e32 v5, v3, v2
	s_nop 0
	v_cndmask_b32_e32 v4, v4, v7, vcc
	v_cndmask_b32_e32 v3, v3, v5, vcc
	v_add_u32_e32 v5, 1, v4
	v_cmp_ge_u32_e32 vcc, v3, v2
	s_nop 1
	v_cndmask_b32_e32 v4, v4, v5, vcc
	v_mul_lo_u32 v3, v2, v4
	v_add_u32_e32 v2, v3, v2
	v_cmp_ne_u32_e32 vcc, v6, v2
	v_mov_b32_e32 v4, v2
	v_mov_b64_e32 v[2:3], s[24:25]
	s_and_saveexec_b64 s[8:9], vcc
	s_cbranch_execz .LBB0_259
	v_mov_b32_e32 v2, 0
	global_load_dword v3, v2, s[24:25] sc1
	s_mov_b64 s[30:31], 0
	s_waitcnt vmcnt(0)
	v_cmp_gt_u32_e32 vcc, v4, v3
	s_and_saveexec_b64 s[28:29], vcc
	s_cbranch_execz .LBB0_258
	s_add_u32 s26, s6, 0x200
	s_addc_u32 s27, s7, 0
	s_mov_b32 s13, 1
	s_branch .LBB0_251

.LBB0_253:
	global_load_dword v3, v2, s[24:25] sc1
	s_add_i32 s13, s13, 1
	s_mov_b64 s[38:39], -1
	s_waitcnt vmcnt(0)
	v_cmp_le_u32_e32 vcc, v4, v3
	s_orn2_b64 s[42:43], vcc, exec
	s_branch .LBB0_250

.LBB0_259:
	s_or_b64 exec, exec, s[8:9]
	s_and_saveexec_b64 s[8:9], s[26:27]
	s_cbranch_execz .LBB0_261
	v_mov_b32_e32 v4, 1
.LBB0_261:
	s_or_b64 exec, exec, s[8:9]
	s_mov_b64 s[8:9], exec
	v_mbcnt_lo_u32_b32 v2, s8, 0
	v_mbcnt_hi_u32_b32 v2, s9, v2
	s_mov_b32 s27, 0
	v_cmp_eq_u32_e32 vcc, 0, v2
	s_waitcnt vmcnt(0)
	s_and_saveexec_b64 s[24:25], vcc
	s_cbranch_execz .LBB0_263
	s_add_i32 s26, s12, 0x900
	s_lshl_b64 s[12:13], s[26:27], 2
	s_add_u32 s6, s6, s12
	s_addc_u32 s7, s7, s13
	s_bcnt1_i32_b64 s8, s[8:9]
	v_mov_b32_e32 v2, 0
	v_mov_b32_e32 v3, s8
	s_nop 0

.LBB0_348:
	s_or_b64 exec, exec, s[8:9]
	v_cvt_f32_u32_e32 v5, v3
	s_waitcnt vmcnt(0)
	v_readfirstlane_b32 s6, v4
	v_sub_u32_e32 v4, 0, v3
	v_rcp_iflag_f32_e32 v5, v5
	v_add_u32_e32 v6, s6, v2
	v_mul_f32_e32 v5, 0x4f7ffffe, v5
	v_cvt_u32_f32_e32 v5, v5
	v_mul_lo_u32 v2, v4, v5
	v_mul_hi_u32 v2, v5, v2
	v_add_u32_e32 v2, v5, v2
	v_mul_hi_u32 v2, v6, v2
	v_mul_lo_u32 v4, v2, v3
	v_sub_u32_e32 v4, v6, v4
	v_add_u32_e32 v5, 1, v2
	v_cmp_ge_u32_e32 vcc, v4, v3
	s_nop 1
	v_cndmask_b32_e32 v2, v2, v5, vcc
	v_sub_u32_e32 v5, v4, v3
	v_cndmask_b32_e32 v4, v4, v5, vcc
	v_add_u32_e32 v5, 1, v2
	v_cmp_ge_u32_e32 vcc, v4, v3
	v_add_u32_e32 v4, 1, v6
	s_nop 0
	v_cndmask_b32_e32 v2, v2, v5, vcc
	v_mul_lo_u32 v5, v3, v2
	v_add_u32_e32 v3, v5, v3
	v_cmp_ne_u32_e32 vcc, v4, v3
	s_and_saveexec_b64 s[6:7], vcc
	s_xor_b64 s[6:7], exec, s[6:7]
	s_cbranch_execz .LBB0_362
	s_movk_i32 s8, 0xd00
	buffer_inv sc1
	s_mov_b32 s9, 0
	s_lshl_b64 s[8:9], s[8:9], 2
	s_add_u32 s10, s4, s8
	s_addc_u32 s11, s5, s9
	s_waitcnt lgkmcnt(0)
	v_mad_u32_u24 v2, v2, v1, v1
	v_mov_b32_e32 v1, 0
	global_load_dword v3, v1, s[10:11] sc1
	s_waitcnt vmcnt(0)
	v_cmp_gt_u32_e32 vcc, v2, v3
	s_and_saveexec_b64 s[8:9], vcc
	s_cbranch_execz .LBB0_361
	s_mov_b32 s13, 1
	s_mov_b64 s[20:21], 0
	s_branch .LBB0_352

.LBB0_354:
	global_load_dword v3, v1, s[10:11] sc1
	s_add_i32 s13, s13, 1
	s_mov_b64 s[26:27], -1
	s_waitcnt vmcnt(0)
	v_cmp_le_u32_e32 vcc, v2, v3
	s_orn2_b64 s[24:25], vcc, exec
	s_branch .LBB0_351

.LBB0_365:
	s_or_b64 exec, exec, s[8:9]
	v_cvt_f32_u32_e32 v4, v1
	s_waitcnt vmcnt(0)
	v_readfirstlane_b32 s6, v3
	s_add_u32 s8, s4, 0x3400
	s_addc_u32 s9, s5, 0
	v_rcp_iflag_f32_e32 v4, v4
	v_add_u32_e32 v2, s6, v2
	v_add_u32_e32 v5, 1, v2
	s_mov_b64 s[10:11], -1
	v_mul_f32_e32 v3, 0x4f7ffffe, v4
	v_cvt_u32_f32_e32 v3, v3
	v_sub_u32_e32 v4, 0, v1
	v_mul_lo_u32 v4, v4, v3
	v_mul_hi_u32 v4, v3, v4
	v_add_u32_e32 v3, v3, v4
	v_mul_hi_u32 v3, v2, v3
	v_mul_lo_u32 v4, v3, v1
	v_sub_u32_e32 v2, v2, v4
	v_add_u32_e32 v6, 1, v3
	v_cmp_ge_u32_e32 vcc, v2, v1
	v_sub_u32_e32 v4, v2, v1
	s_nop 0
	v_cndmask_b32_e32 v3, v3, v6, vcc
	v_cndmask_b32_e32 v2, v2, v4, vcc
	v_add_u32_e32 v4, 1, v3
	v_cmp_ge_u32_e32 vcc, v2, v1
	s_nop 1
	v_cndmask_b32_e32 v4, v3, v4, vcc
	v_mul_lo_u32 v2, v1, v4
	v_add_u32_e32 v1, v2, v1
	v_cmp_ne_u32_e32 vcc, v5, v1
	v_mov_b32_e32 v4, v1
	v_mov_b64_e32 v[2:3], s[8:9]
	s_and_saveexec_b64 s[6:7], vcc
	s_cbranch_execz .LBB0_377
	v_mov_b32_e32 v1, 0
	global_load_dword v2, v1, s[8:9] sc1
	s_mov_b64 s[22:23], 0
	s_waitcnt vmcnt(0)
	v_cmp_gt_u32_e32 vcc, v4, v2
	s_and_saveexec_b64 s[20:21], vcc
	s_cbranch_execz .LBB0_376
	s_add_u32 s10, s4, 0x200
	s_addc_u32 s11, s5, 0
	s_mov_b32 s13, 1
	s_branch .LBB0_369

.LBB0_371:
	global_load_dword v2, v1, s[8:9] sc1
	s_add_i32 s13, s13, 1
	s_mov_b64 s[26:27], -1
	s_waitcnt vmcnt(0)
	v_cmp_le_u32_e32 vcc, v4, v2
	s_orn2_b64 s[30:31], vcc, exec
	s_branch .LBB0_368

.LBB0_377:
	s_or_b64 exec, exec, s[6:7]
	s_and_saveexec_b64 s[6:7], s[10:11]
	s_cbranch_execz .LBB0_379
	v_mov_b32_e32 v1, 1
.LBB0_379:
	s_or_b64 exec, exec, s[6:7]
	s_mov_b64 s[6:7], exec
	v_mbcnt_lo_u32_b32 v1, s6, 0
	v_mbcnt_hi_u32_b32 v1, s7, v1
	s_mov_b32 s11, 0
	v_cmp_eq_u32_e32 vcc, 0, v1
	s_waitcnt vmcnt(0)
	s_and_saveexec_b64 s[8:9], vcc
	s_cbranch_execz .LBB0_381
	s_add_i32 s10, s12, 0x900
	s_lshl_b64 s[10:11], s[10:11], 2
	s_add_u32 s4, s4, s10
	s_addc_u32 s5, s5, s11
	s_bcnt1_i32_b64 s6, s[6:7]
	v_mov_b32_e32 v1, 0
	v_mov_b32_e32 v2, s6
	s_nop 0

.LBB0_483:
	s_or_b64 exec, exec, s[8:9]
	v_cvt_f32_u32_e32 v5, v3
	s_waitcnt vmcnt(0)
	v_readfirstlane_b32 s6, v4
	v_sub_u32_e32 v4, 0, v3
	v_rcp_iflag_f32_e32 v5, v5
	v_add_u32_e32 v6, s6, v2
	v_mul_f32_e32 v5, 0x4f7ffffe, v5
	v_cvt_u32_f32_e32 v5, v5
	v_mul_lo_u32 v2, v4, v5
	v_mul_hi_u32 v2, v5, v2
	v_add_u32_e32 v2, v5, v2
	v_mul_hi_u32 v2, v6, v2
	v_mul_lo_u32 v4, v2, v3
	v_sub_u32_e32 v4, v6, v4
	v_add_u32_e32 v5, 1, v2
	v_cmp_ge_u32_e32 vcc, v4, v3
	s_nop 1
	v_cndmask_b32_e32 v2, v2, v5, vcc
	v_sub_u32_e32 v5, v4, v3
	v_cndmask_b32_e32 v4, v4, v5, vcc
	v_add_u32_e32 v5, 1, v2
	v_cmp_ge_u32_e32 vcc, v4, v3
	v_add_u32_e32 v4, 1, v6
	s_nop 0
	v_cndmask_b32_e32 v2, v2, v5, vcc
	v_mul_lo_u32 v5, v3, v2
	v_add_u32_e32 v3, v5, v3
	v_cmp_ne_u32_e32 vcc, v4, v3
	s_and_saveexec_b64 s[6:7], vcc
	s_xor_b64 s[6:7], exec, s[6:7]
	s_cbranch_execz .LBB0_497
	s_movk_i32 s8, 0xd00
	buffer_inv sc1
	s_mov_b32 s9, 0
	s_lshl_b64 s[8:9], s[8:9], 2
	s_add_u32 s10, s4, s8
	s_addc_u32 s11, s5, s9
	s_waitcnt lgkmcnt(0)
	v_mad_u32_u24 v2, v2, v1, v1
	v_mov_b32_e32 v1, 0
	global_load_dword v3, v1, s[10:11] sc1
	s_waitcnt vmcnt(0)
	v_cmp_gt_u32_e32 vcc, v2, v3
	s_and_saveexec_b64 s[8:9], vcc
	s_cbranch_execz .LBB0_496
	s_mov_b32 s13, 1
	s_mov_b64 s[16:17], 0
	s_branch .LBB0_487

.LBB0_500:
	s_or_b64 exec, exec, s[8:9]
	v_cvt_f32_u32_e32 v4, v1
	s_waitcnt vmcnt(0)
	v_readfirstlane_b32 s6, v3
	s_add_u32 s8, s4, 0x3400
	s_addc_u32 s9, s5, 0
	v_rcp_iflag_f32_e32 v4, v4
	v_add_u32_e32 v2, s6, v2
	v_add_u32_e32 v5, 1, v2
	s_mov_b64 s[10:11], -1
	v_mul_f32_e32 v3, 0x4f7ffffe, v4
	v_cvt_u32_f32_e32 v3, v3
	v_sub_u32_e32 v4, 0, v1
	v_mul_lo_u32 v4, v4, v3
	v_mul_hi_u32 v4, v3, v4
	v_add_u32_e32 v3, v3, v4
	v_mul_hi_u32 v3, v2, v3
	v_mul_lo_u32 v4, v3, v1
	v_sub_u32_e32 v2, v2, v4
	v_add_u32_e32 v6, 1, v3
	v_cmp_ge_u32_e32 vcc, v2, v1
	v_sub_u32_e32 v4, v2, v1
	s_nop 0
	v_cndmask_b32_e32 v3, v3, v6, vcc
	v_cndmask_b32_e32 v2, v2, v4, vcc
	v_add_u32_e32 v4, 1, v3
	v_cmp_ge_u32_e32 vcc, v2, v1
	s_nop 1
	v_cndmask_b32_e32 v4, v3, v4, vcc
	v_mul_lo_u32 v2, v1, v4
	v_add_u32_e32 v1, v2, v1
	v_cmp_ne_u32_e32 vcc, v5, v1
	v_mov_b32_e32 v4, v1
	v_mov_b64_e32 v[2:3], s[8:9]
	s_and_saveexec_b64 s[6:7], vcc
	s_cbranch_execz .LBB0_512
	v_mov_b32_e32 v1, 0
	global_load_dword v2, v1, s[8:9] sc1
	s_mov_b64 s[22:23], 0
	s_waitcnt vmcnt(0)
	v_cmp_gt_u32_e32 vcc, v4, v2
	s_and_saveexec_b64 s[16:17], vcc
	s_cbranch_execz .LBB0_511
	s_add_u32 s10, s4, 0x200
	s_addc_u32 s11, s5, 0
	s_mov_b32 s13, 1
	s_branch .LBB0_504

.LBB0_512:
	s_or_b64 exec, exec, s[6:7]
	s_and_saveexec_b64 s[6:7], s[10:11]
	s_cbranch_execz .LBB0_514
	v_mov_b32_e32 v1, 1
.LBB0_514:
	s_or_b64 exec, exec, s[6:7]
	s_mov_b64 s[6:7], exec
	v_mbcnt_lo_u32_b32 v1, s6, 0
	v_mbcnt_hi_u32_b32 v1, s7, v1
	s_mov_b32 s11, 0
	v_cmp_eq_u32_e32 vcc, 0, v1
	s_waitcnt vmcnt(0)
	s_and_saveexec_b64 s[8:9], vcc
	s_cbranch_execz .LBB0_516
	s_add_i32 s10, s12, 0x900
	s_lshl_b64 s[10:11], s[10:11], 2
	s_add_u32 s4, s4, s10
	s_addc_u32 s5, s5, s11
	s_bcnt1_i32_b64 s6, s[6:7]
	v_mov_b32_e32 v1, 0
	v_mov_b32_e32 v2, s6
	s_nop 0

.LBB0_601:
	s_cmp_lg_u32 s65, 0
	s_cselect_b64 s[38:39], -1, 0
	s_and_b64 vcc, exec, s[38:39]
	s_cbranch_vccz .LBB0_652
	s_lshl_b32 s8, s57, 8
	s_and_b32 s8, s8, 0x300
	s_lshl_b32 s41, s14, 8
	s_waitcnt lgkmcnt(0)
	v_pk_mul_f32 v[160:161], v[134:135], v[146:147]
	v_pk_mul_f32 v[162:163], v[136:137], v[148:149]
	s_add_i32 s8, s8, s35
	s_lshl_b32 s9, s57, 2
	v_or_b32_e32 v166, s41, v181
	v_cvt_pk_bf16_f32 v160, v160, v161
	v_cvt_pk_bf16_f32 v161, v162, v163
	v_pk_mul_f32 v[162:163], v[130:131], v[150:151]
	v_pk_mul_f32 v[164:165], v[132:133], v[152:153]
	s_ashr_i32 s8, s8, 6
	s_and_b32 s9, s9, -16
	v_cvt_pk_bf16_f32 v162, v162, v163
	v_cvt_pk_bf16_f32 v163, v164, v165
	v_ashrrev_i32_e32 v164, 31, v166
	s_add_i32 s8, s9, s8
	v_lshrrev_b32_e32 v164, 27, v164
	s_addk_i32 s8, 0xff90
	v_add_u32_e32 v167, v166, v164
	s_ashr_i32 s9, s8, 31
	v_ashrrev_i32_e32 v164, 5, v167
	s_lshl_b64 s[8:9], s[8:9], 8
	v_ashrrev_i32_e32 v165, 31, v164
	v_lshl_add_u64 v[164:165], s[8:9], 0, v[164:165]
	v_and_b32_e32 v167, 0xffffffe0, v167
	v_lshlrev_b64 v[164:165], 12, v[164:165]
	v_sub_u32_e32 v166, v166, v167
	v_lshl_add_u64 v[164:165], v[158:159], 0, v[164:165]
	v_ashrrev_i32_e32 v167, 31, v166
	v_lshl_add_u64 v[164:165], v[166:167], 1, v[164:165]
	s_cselect_b32 s99, 1, 0
	s_cmp_lg_u32 s4, 0
	s_cbranch_scc0 .Lwt_g3_p0
	global_store_dwordx4 v[164:165], v[160:163], off sc1
	s_branch .Lwt_g3_d0
.Lwt_g3_p0:
	global_store_dwordx4 v[164:165], v[160:163], off
.Lwt_g3_d0:
	s_cmp_lg_u32 s99, 0
	v_or_b32_e32 v166, s41, v182
	v_pk_mul_f32 v[164:165], v[100:101], v[144:145]
	v_pk_mul_f32 v[160:161], v[102:103], v[138:139]
	v_pk_mul_f32 v[162:163], v[104:105], v[140:141]
	v_cvt_pk_bf16_f32 v160, v160, v161
	v_cvt_pk_bf16_f32 v161, v162, v163
	v_pk_mul_f32 v[162:163], v[98:99], v[142:143]
	s_nop 0
	v_cvt_pk_bf16_f32 v162, v162, v163
	v_cvt_pk_bf16_f32 v163, v164, v165
	v_ashrrev_i32_e32 v164, 31, v166
	v_lshrrev_b32_e32 v164, 27, v164
	v_add_u32_e32 v167, v166, v164
	v_ashrrev_i32_e32 v164, 5, v167
	v_ashrrev_i32_e32 v165, 31, v164
	v_lshl_add_u64 v[164:165], s[8:9], 0, v[164:165]
	v_and_b32_e32 v167, 0xffffffe0, v167
	v_lshlrev_b64 v[164:165], 12, v[164:165]
	v_sub_u32_e32 v166, v166, v167
	v_lshl_add_u64 v[164:165], v[158:159], 0, v[164:165]
	v_ashrrev_i32_e32 v167, 31, v166
	v_lshl_add_u64 v[164:165], v[166:167], 1, v[164:165]
	s_cselect_b32 s99, 1, 0
	s_cmp_lg_u32 s4, 0
	s_cbranch_scc0 .Lwt_g3_p1
	global_store_dwordx4 v[164:165], v[160:163], off sc1
	s_branch .Lwt_g3_d1

.Lwt_g3_d1:
	s_cmp_lg_u32 s99, 0
	s_cbranch_execnz .LBB0_653

.LBB0_607:
	s_waitcnt lgkmcnt(0)
	v_pk_mul_f32 v[188:189], v[136:137], v[146:147] op_sel_hi:[1,0]
	v_pk_mul_f32 v[186:187], v[134:135], v[146:147] op_sel_hi:[1,0]
	v_pk_mul_f32 v[190:191], v[132:133], v[146:147] op_sel_hi:[1,0]
	v_pk_mul_f32 v[192:193], v[130:131], v[146:147] op_sel_hi:[1,0]
	v_cvt_pk_bf16_f32 v186, v186, v187
	v_cvt_pk_bf16_f32 v187, v188, v189
	v_cvt_pk_bf16_f32 v188, v192, v193
	v_cvt_pk_bf16_f32 v189, v190, v191
	s_andn2_b64 vcc, exec, s[8:9]
	s_mov_b64 s[8:9], -1
	s_cselect_b32 s99, 1, 0
	s_cmp_lg_u32 s4, 0
	s_cbranch_scc0 .Lwt_g3_p2
	global_store_dwordx4 v[168:169], v[186:189], off sc1
	s_branch .Lwt_g3_d2
.Lwt_g3_p2:
	global_store_dwordx4 v[168:169], v[186:189], off
.Lwt_g3_d2:
	s_cmp_lg_u32 s99, 0
	s_cbranch_vccnz .LBB0_609
	v_or_b32_e32 v161, 0x80, v161
	v_lshrrev_b32_e32 v161, 6, v161
	v_or_b32_e32 v168, s63, v161
	v_ashrrev_i32_e32 v169, 31, v168
	v_lshlrev_b64 v[168:169], 20, v[168:169]
	v_lshl_add_u64 v[168:169], s[10:11], 0, v[168:169]
	v_lshl_add_u64 v[162:163], v[168:169], 0, v[162:163]
	v_mov_b32_e32 v161, v2
	v_lshl_add_u64 v[168:169], v[162:163], 0, v[160:161]
	s_mov_b64 s[8:9], 0

.LBB0_611:
	v_mov_b32_e32 v160, v146
	v_mov_b32_e32 v161, v146
	v_mov_b32_e32 v162, v146
	v_mov_b32_e32 v163, v146
	v_pk_mul_f32 v[164:165], v[104:105], v[162:163]
	v_pk_mul_f32 v[166:167], v[102:103], v[160:161]
	v_pk_mul_f32 v[186:187], v[100:101], v[162:163]
	v_pk_mul_f32 v[162:163], v[98:99], v[160:161]
	v_cvt_pk_bf16_f32 v160, v166, v167
	v_cvt_pk_bf16_f32 v161, v164, v165
	v_cvt_pk_bf16_f32 v162, v162, v163
	v_cvt_pk_bf16_f32 v163, v186, v187
	s_cselect_b32 s99, 1, 0
	s_cmp_lg_u32 s4, 0
	s_cbranch_scc0 .Lwt_g3_p3
	global_store_dwordx4 v[168:169], v[160:163], off sc1
	s_branch .Lwt_g3_d3
.Lwt_g3_p3:
	global_store_dwordx4 v[168:169], v[160:163], off
.Lwt_g3_d3:
	s_cmp_lg_u32 s99, 0
	s_nop 1
	v_cndmask_b32_e64 v160, 0, 1, s[38:39]
	v_cmp_ne_u32_e64 s[8:9], 1, v160
	s_andn2_b64 vcc, exec, s[38:39]
	s_cbranch_vccz .LBB0_654

.LBB0_614:
	s_lshl_b32 s38, s57, 8
	s_and_b32 s38, s38, 0x300
	s_lshl_b32 s41, s14, 8
	s_waitcnt lgkmcnt(0)
	v_pk_mul_f32 v[160:161], v[118:119], v[146:147]
	v_pk_mul_f32 v[162:163], v[120:121], v[148:149]
	s_add_i32 s38, s38, s35
	s_lshl_b32 s39, s57, 2
	v_or_b32_e32 v166, s41, v181
	v_cvt_pk_bf16_f32 v160, v160, v161
	v_cvt_pk_bf16_f32 v161, v162, v163
	v_pk_mul_f32 v[162:163], v[114:115], v[150:151]
	v_pk_mul_f32 v[164:165], v[116:117], v[152:153]
	s_ashr_i32 s38, s38, 6
	s_and_b32 s39, s39, -16
	v_cvt_pk_bf16_f32 v162, v162, v163
	v_cvt_pk_bf16_f32 v163, v164, v165
	v_ashrrev_i32_e32 v164, 31, v166
	s_add_i32 s38, s39, s38
	v_lshrrev_b32_e32 v164, 27, v164
	s_addk_i32 s38, 0xff90
	v_add_u32_e32 v167, v166, v164
	s_ashr_i32 s39, s38, 31
	v_ashrrev_i32_e32 v164, 5, v167
	s_lshl_b64 s[38:39], s[38:39], 8
	v_ashrrev_i32_e32 v165, 31, v164
	v_lshl_add_u64 v[164:165], s[38:39], 0, v[164:165]
	v_and_b32_e32 v167, 0xffffffe0, v167
	v_lshlrev_b64 v[164:165], 12, v[164:165]
	v_sub_u32_e32 v166, v166, v167
	v_lshl_add_u64 v[164:165], v[158:159], 0, v[164:165]
	v_ashrrev_i32_e32 v167, 31, v166
	v_lshl_add_u64 v[164:165], v[166:167], 1, v[164:165]
	s_cselect_b32 s99, 1, 0
	s_cmp_lg_u32 s4, 0
	s_cbranch_scc0 .Lwt_g3_p4
	global_store_dwordx4 v[164:165], v[160:163], off offset:2048 sc1
	s_branch .Lwt_g3_d4
.Lwt_g3_p4:
	global_store_dwordx4 v[164:165], v[160:163], off offset:2048
.Lwt_g3_d4:
	s_cmp_lg_u32 s99, 0
	v_or_b32_e32 v166, s41, v182
	v_pk_mul_f32 v[164:165], v[84:85], v[144:145]
	v_pk_mul_f32 v[160:161], v[86:87], v[138:139]
	v_pk_mul_f32 v[162:163], v[88:89], v[140:141]
	v_cvt_pk_bf16_f32 v160, v160, v161
	v_cvt_pk_bf16_f32 v161, v162, v163
	v_pk_mul_f32 v[162:163], v[82:83], v[142:143]
	s_nop 0
	v_cvt_pk_bf16_f32 v162, v162, v163
	v_cvt_pk_bf16_f32 v163, v164, v165
	v_ashrrev_i32_e32 v164, 31, v166
	v_lshrrev_b32_e32 v164, 27, v164
	v_add_u32_e32 v167, v166, v164
	v_ashrrev_i32_e32 v164, 5, v167
	v_ashrrev_i32_e32 v165, 31, v164
	v_lshl_add_u64 v[164:165], s[38:39], 0, v[164:165]
	v_and_b32_e32 v167, 0xffffffe0, v167
	v_lshlrev_b64 v[164:165], 12, v[164:165]
	v_sub_u32_e32 v166, v166, v167
	v_lshl_add_u64 v[164:165], v[158:159], 0, v[164:165]
	v_ashrrev_i32_e32 v167, 31, v166
	v_lshl_add_u64 v[164:165], v[166:167], 1, v[164:165]
	s_cselect_b32 s99, 1, 0
	s_cmp_lg_u32 s4, 0
	s_cbranch_scc0 .Lwt_g3_p5
	global_store_dwordx4 v[164:165], v[160:163], off offset:2048 sc1
	s_branch .Lwt_g3_d5

.LBB0_619:
	s_waitcnt lgkmcnt(0)
	v_pk_mul_f32 v[188:189], v[120:121], v[148:149] op_sel_hi:[1,0]
	v_pk_mul_f32 v[186:187], v[118:119], v[148:149] op_sel_hi:[1,0]
	v_pk_mul_f32 v[190:191], v[116:117], v[148:149] op_sel_hi:[1,0]
	v_pk_mul_f32 v[192:193], v[114:115], v[148:149] op_sel_hi:[1,0]
	v_cvt_pk_bf16_f32 v186, v186, v187
	v_cvt_pk_bf16_f32 v187, v188, v189
	v_cvt_pk_bf16_f32 v188, v192, v193
	v_cvt_pk_bf16_f32 v189, v190, v191
	s_andn2_b64 vcc, exec, s[38:39]
	s_mov_b64 s[38:39], -1
	s_cselect_b32 s99, 1, 0
	s_cmp_lg_u32 s4, 0
	s_cbranch_scc0 .Lwt_g3_p6
	global_store_dwordx4 v[168:169], v[186:189], off sc1
	s_branch .Lwt_g3_d6

.Lwt_g3_d6:
	s_cmp_lg_u32 s99, 0
	s_cbranch_vccnz .LBB0_621
	v_or_b32_e32 v161, 0x80, v161
	v_lshrrev_b32_e32 v161, 6, v161
	v_or_b32_e32 v168, s63, v161
	v_ashrrev_i32_e32 v169, 31, v168
	v_lshlrev_b64 v[168:169], 20, v[168:169]
	v_lshl_add_u64 v[168:169], s[10:11], 0, v[168:169]
	v_lshl_add_u64 v[162:163], v[168:169], 0, v[162:163]
	v_mov_b32_e32 v161, v2
	v_lshl_add_u64 v[168:169], v[162:163], 0, v[160:161]
	s_mov_b64 s[38:39], 0

.LBB0_623:
	v_mov_b32_e32 v160, v148
	v_mov_b32_e32 v161, v148
	v_mov_b32_e32 v162, v148
	v_mov_b32_e32 v163, v148
	v_pk_mul_f32 v[164:165], v[88:89], v[162:163]
	v_pk_mul_f32 v[166:167], v[86:87], v[160:161]
	v_pk_mul_f32 v[186:187], v[84:85], v[162:163]
	v_pk_mul_f32 v[162:163], v[82:83], v[160:161]
	v_cvt_pk_bf16_f32 v160, v166, v167
	v_cvt_pk_bf16_f32 v161, v164, v165
	v_cvt_pk_bf16_f32 v162, v162, v163
	v_cvt_pk_bf16_f32 v163, v186, v187
	s_cselect_b32 s99, 1, 0
	s_cmp_lg_u32 s4, 0
	s_cbranch_scc0 .Lwt_g3_p7
	global_store_dwordx4 v[168:169], v[160:163], off sc1
	s_branch .Lwt_g3_d7

.Lwt_g3_d7:
	s_cmp_lg_u32 s99, 0
	s_and_b64 vcc, exec, s[8:9]
	s_cbranch_vccz .LBB0_666

.LBB0_626:
	s_lshl_b32 s38, s57, 8
	s_and_b32 s38, s38, 0x300
	s_lshl_b32 s41, s14, 8
	s_waitcnt lgkmcnt(0)
	v_pk_mul_f32 v[160:161], v[70:71], v[146:147]
	v_pk_mul_f32 v[162:163], v[72:73], v[148:149]
	s_add_i32 s38, s38, s56
	s_lshl_b32 s39, s57, 2
	v_or_b32_e32 v166, s41, v181
	v_cvt_pk_bf16_f32 v160, v160, v161
	v_cvt_pk_bf16_f32 v161, v162, v163
	v_pk_mul_f32 v[162:163], v[66:67], v[150:151]
	v_pk_mul_f32 v[164:165], v[68:69], v[152:153]
	s_ashr_i32 s38, s38, 6
	s_and_b32 s39, s39, -16
	v_cvt_pk_bf16_f32 v162, v162, v163
	v_cvt_pk_bf16_f32 v163, v164, v165
	v_ashrrev_i32_e32 v164, 31, v166
	s_add_i32 s38, s39, s38
	v_lshrrev_b32_e32 v164, 27, v164
	s_addk_i32 s38, 0xff90
	v_add_u32_e32 v167, v166, v164
	s_ashr_i32 s39, s38, 31
	v_ashrrev_i32_e32 v164, 5, v167
	s_lshl_b64 s[38:39], s[38:39], 8
	v_ashrrev_i32_e32 v165, 31, v164
	v_lshl_add_u64 v[164:165], s[38:39], 0, v[164:165]
	v_and_b32_e32 v167, 0xffffffe0, v167
	v_lshlrev_b64 v[164:165], 12, v[164:165]
	v_sub_u32_e32 v166, v166, v167
	v_lshl_add_u64 v[164:165], v[158:159], 0, v[164:165]
	v_ashrrev_i32_e32 v167, 31, v166
	v_lshl_add_u64 v[164:165], v[166:167], 1, v[164:165]
	s_cselect_b32 s99, 1, 0
	s_cmp_lg_u32 s4, 0
	s_cbranch_scc0 .Lwt_g3_p8
	global_store_dwordx4 v[164:165], v[160:163], off sc1
	s_branch .Lwt_g3_d8

.Lwt_g3_d8:
	s_cmp_lg_u32 s99, 0
	v_or_b32_e32 v166, s41, v182
	v_pk_mul_f32 v[164:165], v[36:37], v[144:145]
	v_pk_mul_f32 v[160:161], v[38:39], v[138:139]
	v_pk_mul_f32 v[162:163], v[40:41], v[140:141]
	v_cvt_pk_bf16_f32 v160, v160, v161
	v_cvt_pk_bf16_f32 v161, v162, v163
	v_pk_mul_f32 v[162:163], v[34:35], v[142:143]
	s_nop 0
	v_cvt_pk_bf16_f32 v162, v162, v163
	v_cvt_pk_bf16_f32 v163, v164, v165
	v_ashrrev_i32_e32 v164, 31, v166
	v_lshrrev_b32_e32 v164, 27, v164
	v_add_u32_e32 v167, v166, v164
	v_ashrrev_i32_e32 v164, 5, v167
	v_ashrrev_i32_e32 v165, 31, v164
	v_lshl_add_u64 v[164:165], s[38:39], 0, v[164:165]
	v_and_b32_e32 v167, 0xffffffe0, v167
	v_lshlrev_b64 v[164:165], 12, v[164:165]
	v_sub_u32_e32 v166, v166, v167
	v_lshl_add_u64 v[164:165], v[158:159], 0, v[164:165]
	v_ashrrev_i32_e32 v167, 31, v166
	v_lshl_add_u64 v[164:165], v[166:167], 1, v[164:165]
	s_cselect_b32 s99, 1, 0
	s_cmp_lg_u32 s4, 0
	s_cbranch_scc0 .Lwt_g3_p9
	global_store_dwordx4 v[164:165], v[160:163], off sc1
	s_branch .Lwt_g3_d9

.LBB0_631:
	s_waitcnt lgkmcnt(0)
	v_pk_mul_f32 v[188:189], v[72:73], v[138:139] op_sel_hi:[1,0]
	v_pk_mul_f32 v[186:187], v[70:71], v[138:139] op_sel_hi:[1,0]
	v_pk_mul_f32 v[190:191], v[68:69], v[138:139] op_sel_hi:[1,0]
	v_pk_mul_f32 v[192:193], v[66:67], v[138:139] op_sel_hi:[1,0]
	v_cvt_pk_bf16_f32 v186, v186, v187
	v_cvt_pk_bf16_f32 v187, v188, v189
	v_cvt_pk_bf16_f32 v188, v192, v193
	v_cvt_pk_bf16_f32 v189, v190, v191
	s_andn2_b64 vcc, exec, s[38:39]
	s_mov_b64 s[38:39], -1
	s_cselect_b32 s99, 1, 0
	s_cmp_lg_u32 s4, 0
	s_cbranch_scc0 .Lwt_g3_p10
	global_store_dwordx4 v[168:169], v[186:189], off sc1
	s_branch .Lwt_g3_d10

.LBB0_635:
	v_mov_b32_e32 v160, v138
	v_mov_b32_e32 v161, v138
	v_mov_b32_e32 v162, v138
	v_mov_b32_e32 v163, v138
	v_pk_mul_f32 v[164:165], v[40:41], v[162:163]
	v_pk_mul_f32 v[166:167], v[38:39], v[160:161]
	v_pk_mul_f32 v[186:187], v[36:37], v[162:163]
	v_pk_mul_f32 v[162:163], v[34:35], v[160:161]
	v_cvt_pk_bf16_f32 v160, v166, v167
	v_cvt_pk_bf16_f32 v161, v164, v165
	v_cvt_pk_bf16_f32 v162, v162, v163
	v_cvt_pk_bf16_f32 v163, v186, v187
	s_cselect_b32 s99, 1, 0
	s_cmp_lg_u32 s4, 0
	s_cbranch_scc0 .Lwt_g3_p11
	global_store_dwordx4 v[168:169], v[160:163], off sc1
	s_branch .Lwt_g3_d11

.LBB0_638:
	s_lshl_b32 s38, s57, 8
	s_and_b32 s38, s38, 0x300
	s_lshl_b32 s41, s14, 8
	s_waitcnt lgkmcnt(0)
	v_pk_mul_f32 v[160:161], v[54:55], v[146:147]
	v_pk_mul_f32 v[162:163], v[56:57], v[148:149]
	s_add_i32 s38, s38, s56
	s_lshl_b32 s39, s57, 2
	v_or_b32_e32 v166, s41, v181
	v_cvt_pk_bf16_f32 v160, v160, v161
	v_cvt_pk_bf16_f32 v161, v162, v163
	v_pk_mul_f32 v[162:163], v[50:51], v[150:151]
	v_pk_mul_f32 v[164:165], v[52:53], v[152:153]
	s_ashr_i32 s38, s38, 6
	s_and_b32 s39, s39, -16
	v_cvt_pk_bf16_f32 v162, v162, v163
	v_cvt_pk_bf16_f32 v163, v164, v165
	v_ashrrev_i32_e32 v164, 31, v166
	s_add_i32 s38, s39, s38
	v_lshrrev_b32_e32 v164, 27, v164
	s_addk_i32 s38, 0xff90
	v_add_u32_e32 v167, v166, v164
	s_ashr_i32 s39, s38, 31
	v_ashrrev_i32_e32 v164, 5, v167
	s_lshl_b64 s[38:39], s[38:39], 8
	v_ashrrev_i32_e32 v165, 31, v164
	v_lshl_add_u64 v[164:165], s[38:39], 0, v[164:165]
	v_and_b32_e32 v167, 0xffffffe0, v167
	v_lshlrev_b64 v[164:165], 12, v[164:165]
	v_sub_u32_e32 v166, v166, v167
	v_lshl_add_u64 v[164:165], v[158:159], 0, v[164:165]
	v_ashrrev_i32_e32 v167, 31, v166
	v_lshl_add_u64 v[164:165], v[166:167], 1, v[164:165]
	s_cselect_b32 s99, 1, 0
	s_cmp_lg_u32 s4, 0
	s_cbranch_scc0 .Lwt_g3_p12
	global_store_dwordx4 v[164:165], v[160:163], off offset:2048 sc1
	s_branch .Lwt_g3_d12

.Lwt_g3_d12:
	s_cmp_lg_u32 s99, 0
	v_or_b32_e32 v166, s41, v182
	v_pk_mul_f32 v[164:165], v[20:21], v[144:145]
	v_pk_mul_f32 v[160:161], v[22:23], v[138:139]
	v_pk_mul_f32 v[162:163], v[24:25], v[140:141]
	v_cvt_pk_bf16_f32 v160, v160, v161
	v_cvt_pk_bf16_f32 v161, v162, v163
	v_pk_mul_f32 v[162:163], v[18:19], v[142:143]
	s_nop 0
	v_cvt_pk_bf16_f32 v162, v162, v163
	v_cvt_pk_bf16_f32 v163, v164, v165
	v_ashrrev_i32_e32 v164, 31, v166
	v_lshrrev_b32_e32 v164, 27, v164
	v_add_u32_e32 v167, v166, v164
	v_ashrrev_i32_e32 v164, 5, v167
	v_ashrrev_i32_e32 v165, 31, v164
	v_lshl_add_u64 v[164:165], s[38:39], 0, v[164:165]
	v_and_b32_e32 v167, 0xffffffe0, v167
	v_lshlrev_b64 v[164:165], 12, v[164:165]
	v_sub_u32_e32 v166, v166, v167
	v_lshl_add_u64 v[164:165], v[158:159], 0, v[164:165]
	v_ashrrev_i32_e32 v167, 31, v166
	v_lshl_add_u64 v[164:165], v[166:167], 1, v[164:165]
	s_cselect_b32 s99, 1, 0
	s_cmp_lg_u32 s4, 0
	s_cbranch_scc0 .Lwt_g3_p13
	global_store_dwordx4 v[164:165], v[160:163], off offset:2048 sc1
	s_branch .Lwt_g3_d13

.LBB0_643:
	s_waitcnt lgkmcnt(0)
	v_pk_mul_f32 v[188:189], v[56:57], v[140:141] op_sel_hi:[1,0]
	v_pk_mul_f32 v[186:187], v[54:55], v[140:141] op_sel_hi:[1,0]
	v_pk_mul_f32 v[190:191], v[52:53], v[140:141] op_sel_hi:[1,0]
	v_pk_mul_f32 v[192:193], v[50:51], v[140:141] op_sel_hi:[1,0]
	v_cvt_pk_bf16_f32 v186, v186, v187
	v_cvt_pk_bf16_f32 v187, v188, v189
	v_cvt_pk_bf16_f32 v188, v192, v193
	v_cvt_pk_bf16_f32 v189, v190, v191
	s_andn2_b64 vcc, exec, s[38:39]
	s_mov_b64 s[38:39], -1
	s_cselect_b32 s99, 1, 0
	s_cmp_lg_u32 s4, 0
	s_cbranch_scc0 .Lwt_g3_p14
	global_store_dwordx4 v[168:169], v[186:189], off sc1
	s_branch .Lwt_g3_d14

.LBB0_647:
	v_mov_b32_e32 v160, v140
	v_mov_b32_e32 v161, v140
	v_mov_b32_e32 v162, v140
	v_mov_b32_e32 v163, v140
	v_pk_mul_f32 v[164:165], v[24:25], v[162:163]
	v_pk_mul_f32 v[166:167], v[22:23], v[160:161]
	v_pk_mul_f32 v[186:187], v[20:21], v[162:163]
	v_pk_mul_f32 v[162:163], v[18:19], v[160:161]
	v_cvt_pk_bf16_f32 v160, v166, v167
	v_cvt_pk_bf16_f32 v161, v164, v165
	v_cvt_pk_bf16_f32 v162, v162, v163
	v_cvt_pk_bf16_f32 v163, v186, v187
	s_cselect_b32 s99, 1, 0
	s_cmp_lg_u32 s4, 0
	s_cbranch_scc0 .Lwt_g3_p15
	global_store_dwordx4 v[168:169], v[160:163], off sc1
	s_branch .Lwt_g3_d15

.LBB0_654:
	s_lshl_b32 s38, s57, 8
	s_and_b32 s38, s38, 0x300
	s_lshl_b32 s41, s14, 8
	s_waitcnt lgkmcnt(0)
	v_pk_mul_f32 v[160:161], v[126:127], v[146:147]
	v_pk_mul_f32 v[162:163], v[128:129], v[148:149]
	s_add_i32 s38, s38, s35
	s_lshl_b32 s39, s57, 2
	v_or_b32_e32 v166, s41, v181
	v_cvt_pk_bf16_f32 v160, v160, v161
	v_cvt_pk_bf16_f32 v161, v162, v163
	v_pk_mul_f32 v[162:163], v[122:123], v[150:151]
	v_pk_mul_f32 v[164:165], v[124:125], v[152:153]
	s_ashr_i32 s38, s38, 6
	s_and_b32 s39, s39, -16
	v_cvt_pk_bf16_f32 v162, v162, v163
	v_cvt_pk_bf16_f32 v163, v164, v165
	v_ashrrev_i32_e32 v164, 31, v166
	s_add_i32 s38, s39, s38
	v_lshrrev_b32_e32 v164, 27, v164
	s_addk_i32 s38, 0xff90
	v_add_u32_e32 v167, v166, v164
	s_ashr_i32 s39, s38, 31
	v_ashrrev_i32_e32 v164, 5, v167
	s_lshl_b64 s[38:39], s[38:39], 8
	v_ashrrev_i32_e32 v165, 31, v164
	v_lshl_add_u64 v[164:165], s[38:39], 0, v[164:165]
	v_and_b32_e32 v167, 0xffffffe0, v167
	v_lshlrev_b64 v[164:165], 12, v[164:165]
	v_sub_u32_e32 v166, v166, v167
	v_lshl_add_u64 v[164:165], v[158:159], 0, v[164:165]
	v_ashrrev_i32_e32 v167, 31, v166
	v_lshl_add_u64 v[164:165], v[166:167], 1, v[164:165]
	s_cselect_b32 s99, 1, 0
	s_cmp_lg_u32 s4, 0
	s_cbranch_scc0 .Lwt_g3_p16
	global_store_dwordx4 v[164:165], v[160:163], off offset:1024 sc1
	s_branch .Lwt_g3_d16
.Lwt_g3_p16:
	global_store_dwordx4 v[164:165], v[160:163], off offset:1024
.Lwt_g3_d16:
	s_cmp_lg_u32 s99, 0
	v_or_b32_e32 v166, s41, v182
	v_pk_mul_f32 v[164:165], v[92:93], v[144:145]
	v_pk_mul_f32 v[160:161], v[94:95], v[138:139]
	v_pk_mul_f32 v[162:163], v[96:97], v[140:141]
	v_cvt_pk_bf16_f32 v160, v160, v161
	v_cvt_pk_bf16_f32 v161, v162, v163
	v_pk_mul_f32 v[162:163], v[90:91], v[142:143]
	s_nop 0
	v_cvt_pk_bf16_f32 v162, v162, v163
	v_cvt_pk_bf16_f32 v163, v164, v165
	v_ashrrev_i32_e32 v164, 31, v166
	v_lshrrev_b32_e32 v164, 27, v164
	v_add_u32_e32 v167, v166, v164
	v_ashrrev_i32_e32 v164, 5, v167
	v_ashrrev_i32_e32 v165, 31, v164
	v_lshl_add_u64 v[164:165], s[38:39], 0, v[164:165]
	v_and_b32_e32 v167, 0xffffffe0, v167
	v_lshlrev_b64 v[164:165], 12, v[164:165]
	v_sub_u32_e32 v166, v166, v167
	v_lshl_add_u64 v[164:165], v[158:159], 0, v[164:165]
	v_ashrrev_i32_e32 v167, 31, v166
	v_lshl_add_u64 v[164:165], v[166:167], 1, v[164:165]
	s_cselect_b32 s99, 1, 0
	s_cmp_lg_u32 s4, 0
	s_cbranch_scc0 .Lwt_g3_p17
	global_store_dwordx4 v[164:165], v[160:163], off offset:1024 sc1
	s_branch .Lwt_g3_d17

.LBB0_659:
	s_waitcnt lgkmcnt(0)
	v_pk_mul_f32 v[188:189], v[128:129], v[146:147] op_sel:[0,1]
	v_pk_mul_f32 v[186:187], v[126:127], v[146:147] op_sel:[0,1]
	v_pk_mul_f32 v[190:191], v[124:125], v[146:147] op_sel:[0,1]
	v_pk_mul_f32 v[192:193], v[122:123], v[146:147] op_sel:[0,1]
	v_cvt_pk_bf16_f32 v186, v186, v187
	v_cvt_pk_bf16_f32 v187, v188, v189
	v_cvt_pk_bf16_f32 v188, v192, v193
	v_cvt_pk_bf16_f32 v189, v190, v191
	s_andn2_b64 vcc, exec, s[38:39]
	s_mov_b64 s[38:39], -1
	s_cselect_b32 s99, 1, 0
	s_cmp_lg_u32 s4, 0
	s_cbranch_scc0 .Lwt_g3_p18
	global_store_dwordx4 v[168:169], v[186:189], off sc1
	s_branch .Lwt_g3_d18

.LBB0_663:
	v_mov_b32_e32 v160, v147
	v_mov_b32_e32 v161, v147
	v_mov_b32_e32 v162, v147
	v_mov_b32_e32 v163, v147
	v_pk_mul_f32 v[164:165], v[96:97], v[162:163]
	v_pk_mul_f32 v[166:167], v[94:95], v[160:161]
	v_pk_mul_f32 v[186:187], v[92:93], v[162:163]
	v_pk_mul_f32 v[162:163], v[90:91], v[160:161]
	v_cvt_pk_bf16_f32 v160, v166, v167
	v_cvt_pk_bf16_f32 v161, v164, v165
	v_cvt_pk_bf16_f32 v162, v162, v163
	v_cvt_pk_bf16_f32 v163, v186, v187
	s_cselect_b32 s99, 1, 0
	s_cmp_lg_u32 s4, 0
	s_cbranch_scc0 .Lwt_g3_p19
	global_store_dwordx4 v[168:169], v[160:163], off sc1
	s_branch .Lwt_g3_d19

.LBB0_666:
	s_lshl_b32 s38, s57, 8
	s_and_b32 s38, s38, 0x300
	s_lshl_b32 s41, s14, 8
	s_waitcnt lgkmcnt(0)
	v_pk_mul_f32 v[160:161], v[110:111], v[146:147]
	v_pk_mul_f32 v[162:163], v[112:113], v[148:149]
	s_add_i32 s38, s38, s35
	s_lshl_b32 s39, s57, 2
	v_or_b32_e32 v166, s41, v181
	v_cvt_pk_bf16_f32 v160, v160, v161
	v_cvt_pk_bf16_f32 v161, v162, v163
	v_pk_mul_f32 v[162:163], v[106:107], v[150:151]
	v_pk_mul_f32 v[164:165], v[108:109], v[152:153]
	s_ashr_i32 s38, s38, 6
	s_and_b32 s39, s39, -16
	v_cvt_pk_bf16_f32 v162, v162, v163
	v_cvt_pk_bf16_f32 v163, v164, v165
	v_ashrrev_i32_e32 v164, 31, v166
	s_add_i32 s38, s39, s38
	v_lshrrev_b32_e32 v164, 27, v164
	s_addk_i32 s38, 0xff90
	v_add_u32_e32 v167, v166, v164
	s_ashr_i32 s39, s38, 31
	v_ashrrev_i32_e32 v164, 5, v167
	s_lshl_b64 s[38:39], s[38:39], 8
	v_ashrrev_i32_e32 v165, 31, v164
	v_lshl_add_u64 v[164:165], s[38:39], 0, v[164:165]
	v_and_b32_e32 v167, 0xffffffe0, v167
	v_lshlrev_b64 v[164:165], 12, v[164:165]
	v_sub_u32_e32 v166, v166, v167
	v_lshl_add_u64 v[164:165], v[158:159], 0, v[164:165]
	v_ashrrev_i32_e32 v167, 31, v166
	v_lshl_add_u64 v[164:165], v[166:167], 1, v[164:165]
	s_cselect_b32 s99, 1, 0
	s_cmp_lg_u32 s4, 0
	s_cbranch_scc0 .Lwt_g3_p20
	global_store_dwordx4 v[164:165], v[160:163], off offset:3072 sc1
	s_branch .Lwt_g3_d20
.Lwt_g3_p20:
	global_store_dwordx4 v[164:165], v[160:163], off offset:3072
.Lwt_g3_d20:
	s_cmp_lg_u32 s99, 0
	v_or_b32_e32 v166, s41, v182
	v_pk_mul_f32 v[164:165], v[76:77], v[144:145]
	v_pk_mul_f32 v[160:161], v[78:79], v[138:139]
	v_pk_mul_f32 v[162:163], v[80:81], v[140:141]
	v_cvt_pk_bf16_f32 v160, v160, v161
	v_cvt_pk_bf16_f32 v161, v162, v163
	v_pk_mul_f32 v[162:163], v[74:75], v[142:143]
	s_nop 0
	v_cvt_pk_bf16_f32 v162, v162, v163
	v_cvt_pk_bf16_f32 v163, v164, v165
	v_ashrrev_i32_e32 v164, 31, v166
	v_lshrrev_b32_e32 v164, 27, v164
	v_add_u32_e32 v167, v166, v164
	v_ashrrev_i32_e32 v164, 5, v167
	v_ashrrev_i32_e32 v165, 31, v164
	v_lshl_add_u64 v[164:165], s[38:39], 0, v[164:165]
	v_and_b32_e32 v167, 0xffffffe0, v167
	v_lshlrev_b64 v[164:165], 12, v[164:165]
	v_sub_u32_e32 v166, v166, v167
	v_lshl_add_u64 v[164:165], v[158:159], 0, v[164:165]
	v_ashrrev_i32_e32 v167, 31, v166
	v_lshl_add_u64 v[164:165], v[166:167], 1, v[164:165]
	s_cselect_b32 s99, 1, 0
	s_cmp_lg_u32 s4, 0
	s_cbranch_scc0 .Lwt_g3_p21
	global_store_dwordx4 v[164:165], v[160:163], off offset:3072 sc1
	s_branch .Lwt_g3_d21

.LBB0_671:
	s_waitcnt lgkmcnt(0)
	v_pk_mul_f32 v[188:189], v[112:113], v[148:149] op_sel:[0,1]
	v_pk_mul_f32 v[186:187], v[110:111], v[148:149] op_sel:[0,1]
	v_pk_mul_f32 v[190:191], v[108:109], v[148:149] op_sel:[0,1]
	v_pk_mul_f32 v[192:193], v[106:107], v[148:149] op_sel:[0,1]
	v_cvt_pk_bf16_f32 v186, v186, v187
	v_cvt_pk_bf16_f32 v187, v188, v189
	v_cvt_pk_bf16_f32 v188, v192, v193
	v_cvt_pk_bf16_f32 v189, v190, v191
	s_andn2_b64 vcc, exec, s[38:39]
	s_mov_b64 s[38:39], -1
	s_cselect_b32 s99, 1, 0
	s_cmp_lg_u32 s4, 0
	s_cbranch_scc0 .Lwt_g3_p22
	global_store_dwordx4 v[168:169], v[186:189], off sc1
	s_branch .Lwt_g3_d22

.LBB0_675:
	v_mov_b32_e32 v160, v149
	v_mov_b32_e32 v161, v149
	v_mov_b32_e32 v162, v149
	v_mov_b32_e32 v163, v149
	v_pk_mul_f32 v[164:165], v[80:81], v[162:163]
	v_pk_mul_f32 v[166:167], v[78:79], v[160:161]
	v_pk_mul_f32 v[186:187], v[76:77], v[162:163]
	v_pk_mul_f32 v[162:163], v[74:75], v[160:161]
	v_cvt_pk_bf16_f32 v160, v166, v167
	v_cvt_pk_bf16_f32 v161, v164, v165
	v_cvt_pk_bf16_f32 v162, v162, v163
	v_cvt_pk_bf16_f32 v163, v186, v187
	s_cselect_b32 s99, 1, 0
	s_cmp_lg_u32 s4, 0
	s_cbranch_scc0 .Lwt_g3_p23
	global_store_dwordx4 v[168:169], v[160:163], off sc1
	s_branch .Lwt_g3_d23

.LBB0_678:
	s_lshl_b32 s38, s57, 8
	s_and_b32 s38, s38, 0x300
	s_lshl_b32 s41, s14, 8
	s_waitcnt lgkmcnt(0)
	v_pk_mul_f32 v[160:161], v[62:63], v[146:147]
	v_pk_mul_f32 v[162:163], v[64:65], v[148:149]
	s_add_i32 s38, s38, s56
	s_lshl_b32 s39, s57, 2
	v_or_b32_e32 v166, s41, v181
	v_cvt_pk_bf16_f32 v160, v160, v161
	v_cvt_pk_bf16_f32 v161, v162, v163
	v_pk_mul_f32 v[162:163], v[58:59], v[150:151]
	v_pk_mul_f32 v[164:165], v[60:61], v[152:153]
	s_ashr_i32 s38, s38, 6
	s_and_b32 s39, s39, -16
	v_cvt_pk_bf16_f32 v162, v162, v163
	v_cvt_pk_bf16_f32 v163, v164, v165
	v_ashrrev_i32_e32 v164, 31, v166
	s_add_i32 s38, s39, s38
	v_lshrrev_b32_e32 v164, 27, v164
	s_addk_i32 s38, 0xff90
	v_add_u32_e32 v167, v166, v164
	s_ashr_i32 s39, s38, 31
	v_ashrrev_i32_e32 v164, 5, v167
	s_lshl_b64 s[38:39], s[38:39], 8
	v_ashrrev_i32_e32 v165, 31, v164
	v_lshl_add_u64 v[164:165], s[38:39], 0, v[164:165]
	v_and_b32_e32 v167, 0xffffffe0, v167
	v_lshlrev_b64 v[164:165], 12, v[164:165]
	v_sub_u32_e32 v166, v166, v167
	v_lshl_add_u64 v[164:165], v[158:159], 0, v[164:165]
	v_ashrrev_i32_e32 v167, 31, v166
	v_lshl_add_u64 v[164:165], v[166:167], 1, v[164:165]
	s_cselect_b32 s99, 1, 0
	s_cmp_lg_u32 s4, 0
	s_cbranch_scc0 .Lwt_g3_p24
	global_store_dwordx4 v[164:165], v[160:163], off offset:1024 sc1
	s_branch .Lwt_g3_d24

.Lwt_g3_d24:
	s_cmp_lg_u32 s99, 0
	v_or_b32_e32 v166, s41, v182
	v_pk_mul_f32 v[164:165], v[28:29], v[144:145]
	v_pk_mul_f32 v[160:161], v[30:31], v[138:139]
	v_pk_mul_f32 v[162:163], v[32:33], v[140:141]
	v_cvt_pk_bf16_f32 v160, v160, v161
	v_cvt_pk_bf16_f32 v161, v162, v163
	v_pk_mul_f32 v[162:163], v[26:27], v[142:143]
	s_nop 0
	v_cvt_pk_bf16_f32 v162, v162, v163
	v_cvt_pk_bf16_f32 v163, v164, v165
	v_ashrrev_i32_e32 v164, 31, v166
	v_lshrrev_b32_e32 v164, 27, v164
	v_add_u32_e32 v167, v166, v164
	v_ashrrev_i32_e32 v164, 5, v167
	v_ashrrev_i32_e32 v165, 31, v164
	v_lshl_add_u64 v[164:165], s[38:39], 0, v[164:165]
	v_and_b32_e32 v167, 0xffffffe0, v167
	v_lshlrev_b64 v[164:165], 12, v[164:165]
	v_sub_u32_e32 v166, v166, v167
	v_lshl_add_u64 v[164:165], v[158:159], 0, v[164:165]
	v_ashrrev_i32_e32 v167, 31, v166
	v_lshl_add_u64 v[164:165], v[166:167], 1, v[164:165]
	s_cselect_b32 s99, 1, 0
	s_cmp_lg_u32 s4, 0
	s_cbranch_scc0 .Lwt_g3_p25
	global_store_dwordx4 v[164:165], v[160:163], off offset:1024 sc1
	s_branch .Lwt_g3_d25

.LBB0_683:
	s_waitcnt lgkmcnt(0)
	v_pk_mul_f32 v[188:189], v[64:65], v[138:139] op_sel:[0,1]
	v_pk_mul_f32 v[186:187], v[62:63], v[138:139] op_sel:[0,1]
	v_pk_mul_f32 v[190:191], v[60:61], v[138:139] op_sel:[0,1]
	v_pk_mul_f32 v[192:193], v[58:59], v[138:139] op_sel:[0,1]
	v_cvt_pk_bf16_f32 v186, v186, v187
	v_cvt_pk_bf16_f32 v187, v188, v189
	v_cvt_pk_bf16_f32 v188, v192, v193
	v_cvt_pk_bf16_f32 v189, v190, v191
	s_andn2_b64 vcc, exec, s[38:39]
	s_mov_b64 s[38:39], -1
	s_cselect_b32 s99, 1, 0
	s_cmp_lg_u32 s4, 0
	s_cbranch_scc0 .Lwt_g3_p26
	global_store_dwordx4 v[168:169], v[186:189], off sc1
	s_branch .Lwt_g3_d26

.LBB0_687:
	v_mov_b32_e32 v160, v139
	v_mov_b32_e32 v161, v139
	v_mov_b32_e32 v162, v139
	v_mov_b32_e32 v163, v139
	v_pk_mul_f32 v[164:165], v[32:33], v[162:163]
	v_pk_mul_f32 v[166:167], v[30:31], v[160:161]
	v_pk_mul_f32 v[186:187], v[28:29], v[162:163]
	v_pk_mul_f32 v[162:163], v[26:27], v[160:161]
	v_cvt_pk_bf16_f32 v160, v166, v167
	v_cvt_pk_bf16_f32 v161, v164, v165
	v_cvt_pk_bf16_f32 v162, v162, v163
	v_cvt_pk_bf16_f32 v163, v186, v187
	s_cselect_b32 s99, 1, 0
	s_cmp_lg_u32 s4, 0
	s_cbranch_scc0 .Lwt_g3_p27
	global_store_dwordx4 v[168:169], v[160:163], off sc1
	s_branch .Lwt_g3_d27

.LBB0_690:
	s_lshl_b32 s8, s57, 8
	s_and_b32 s8, s8, 0x300
	s_lshl_b32 s38, s14, 8
	s_waitcnt lgkmcnt(0)
	v_pk_mul_f32 v[146:147], v[46:47], v[146:147]
	v_pk_mul_f32 v[148:149], v[48:49], v[148:149]
	s_add_i32 s8, s8, s56
	s_lshl_b32 s9, s57, 2
	v_or_b32_e32 v160, s38, v181
	v_cvt_pk_bf16_f32 v146, v146, v147
	v_cvt_pk_bf16_f32 v147, v148, v149
	v_pk_mul_f32 v[148:149], v[42:43], v[150:151]
	v_pk_mul_f32 v[150:151], v[44:45], v[152:153]
	s_ashr_i32 s8, s8, 6
	s_and_b32 s9, s9, -16
	v_cvt_pk_bf16_f32 v148, v148, v149
	v_cvt_pk_bf16_f32 v149, v150, v151
	v_ashrrev_i32_e32 v150, 31, v160
	s_add_i32 s8, s9, s8
	v_lshrrev_b32_e32 v150, 27, v150
	s_addk_i32 s8, 0xff90
	v_add_u32_e32 v152, v160, v150
	s_ashr_i32 s9, s8, 31
	v_ashrrev_i32_e32 v150, 5, v152
	s_lshl_b64 s[8:9], s[8:9], 8
	v_ashrrev_i32_e32 v151, 31, v150
	v_lshl_add_u64 v[150:151], s[8:9], 0, v[150:151]
	v_and_b32_e32 v152, 0xffffffe0, v152
	v_lshlrev_b64 v[150:151], 12, v[150:151]
	v_sub_u32_e32 v152, v160, v152
	v_lshl_add_u64 v[150:151], v[158:159], 0, v[150:151]
	v_ashrrev_i32_e32 v153, 31, v152
	v_lshl_add_u64 v[150:151], v[152:153], 1, v[150:151]
	v_pk_mul_f32 v[138:139], v[14:15], v[138:139]
	s_cselect_b32 s99, 1, 0
	s_cmp_lg_u32 s4, 0
	s_cbranch_scc0 .Lwt_g3_p28
	global_store_dwordx4 v[150:151], v[146:149], off offset:3072 sc1
	s_branch .Lwt_g3_d28
.Lwt_g3_p28:
	global_store_dwordx4 v[150:151], v[146:149], off offset:3072
.Lwt_g3_d28:
	s_cmp_lg_u32 s99, 0
	v_or_b32_e32 v150, s38, v182
	s_nop 0
	v_cvt_pk_bf16_f32 v146, v138, v139
	v_pk_mul_f32 v[138:139], v[16:17], v[140:141]
	s_nop 0
	v_cvt_pk_bf16_f32 v147, v138, v139
	v_pk_mul_f32 v[138:139], v[10:11], v[142:143]
	s_nop 0
	v_cvt_pk_bf16_f32 v148, v138, v139
	v_pk_mul_f32 v[138:139], v[12:13], v[144:145]
	s_nop 0
	v_cvt_pk_bf16_f32 v149, v138, v139
	v_ashrrev_i32_e32 v138, 31, v150
	v_lshrrev_b32_e32 v138, 27, v138
	v_add_u32_e32 v142, v150, v138
	v_ashrrev_i32_e32 v138, 5, v142
	v_ashrrev_i32_e32 v139, 31, v138
	v_lshl_add_u64 v[138:139], s[8:9], 0, v[138:139]
	v_and_b32_e32 v142, 0xffffffe0, v142
	v_lshlrev_b64 v[138:139], 12, v[138:139]
	v_sub_u32_e32 v142, v150, v142
	v_lshl_add_u64 v[138:139], v[158:159], 0, v[138:139]
	v_ashrrev_i32_e32 v143, 31, v142
	v_lshl_add_u64 v[138:139], v[142:143], 1, v[138:139]
	s_cselect_b32 s99, 1, 0
	s_cmp_lg_u32 s4, 0
	s_cbranch_scc0 .Lwt_g3_p29
	global_store_dwordx4 v[138:139], v[146:149], off offset:3072 sc1
	s_branch .Lwt_g3_d29
.Lwt_g3_p29:
	global_store_dwordx4 v[138:139], v[146:149], off offset:3072

.LBB0_695:
	v_pk_mul_f32 v[152:153], v[48:49], v[140:141] op_sel:[0,1]
	v_pk_mul_f32 v[150:151], v[46:47], v[140:141] op_sel:[0,1]
	v_pk_mul_f32 v[160:161], v[44:45], v[140:141] op_sel:[0,1]
	v_pk_mul_f32 v[162:163], v[42:43], v[140:141] op_sel:[0,1]
	v_cvt_pk_bf16_f32 v150, v150, v151
	v_cvt_pk_bf16_f32 v151, v152, v153
	v_cvt_pk_bf16_f32 v152, v162, v163
	v_cvt_pk_bf16_f32 v153, v160, v161
	s_andn2_b64 vcc, exec, s[8:9]
	s_mov_b64 s[8:9], -1
	s_cselect_b32 s99, 1, 0
	s_cmp_lg_u32 s4, 0
	s_cbranch_scc0 .Lwt_g3_p30
	global_store_dwordx4 v[148:149], v[150:153], off sc1
	s_branch .Lwt_g3_d30
.Lwt_g3_p30:
	global_store_dwordx4 v[148:149], v[150:153], off
.Lwt_g3_d30:
	s_cmp_lg_u32 s99, 0
	s_cbranch_vccnz .LBB0_697
	v_or_b32_e32 v139, 0x80, v139
	v_lshrrev_b32_e32 v139, 6, v139
	v_or_b32_e32 v148, s63, v139
	v_ashrrev_i32_e32 v149, 31, v148
	v_lshlrev_b64 v[148:149], 20, v[148:149]
	v_lshl_add_u64 v[148:149], s[10:11], 0, v[148:149]
	v_lshl_add_u64 v[142:143], v[148:149], 0, v[142:143]
	v_mov_b32_e32 v139, v2
	v_lshl_add_u64 v[148:149], v[142:143], 0, v[138:139]
	s_mov_b64 s[8:9], 0

.LBB0_699:
	v_mov_b32_e32 v140, v141
	v_mov_b32_e32 v138, v141
	v_mov_b32_e32 v139, v141
	v_pk_mul_f32 v[142:143], v[16:17], v[138:139]
	v_pk_mul_f32 v[144:145], v[14:15], v[140:141]
	v_pk_mul_f32 v[146:147], v[12:13], v[138:139]
	v_pk_mul_f32 v[140:141], v[10:11], v[140:141]
	v_cvt_pk_bf16_f32 v138, v144, v145
	v_cvt_pk_bf16_f32 v139, v142, v143
	v_cvt_pk_bf16_f32 v140, v140, v141
	v_cvt_pk_bf16_f32 v141, v146, v147
	s_cselect_b32 s99, 1, 0
	s_cmp_lg_u32 s4, 0
	s_cbranch_scc0 .Lwt_g3_p31
	global_store_dwordx4 v[148:149], v[138:141], off sc1
	s_branch .Lwt_g3_d31
.Lwt_g3_p31:
	global_store_dwordx4 v[148:149], v[138:141], off
.Lwt_g3_d31:
	s_cmp_lg_u32 s99, 0
	s_add_u32 s8, s83, 0xffffff00
	s_addc_u32 s9, s62, -1
	s_andn2_b64 vcc, exec, s[6:7]
	s_cbranch_vccz .LBB0_650

.LBB0_720:
	s_or_b64 exec, exec, s[36:37]
	v_cvt_f32_u32_e32 v10, v4
	s_waitcnt vmcnt(0)
	v_readfirstlane_b32 s8, v5
	v_sub_u32_e32 v5, 0, v4
	v_rcp_iflag_f32_e32 v10, v10
	v_add_u32_e32 v11, s8, v3
	v_mul_f32_e32 v10, 0x4f7ffffe, v10
	v_cvt_u32_f32_e32 v10, v10
	v_mul_lo_u32 v3, v5, v10
	v_mul_hi_u32 v3, v10, v3
	v_add_u32_e32 v3, v10, v3
	v_mul_hi_u32 v3, v11, v3
	v_mul_lo_u32 v5, v3, v4
	v_sub_u32_e32 v5, v11, v5
	v_add_u32_e32 v10, 1, v3
	v_cmp_ge_u32_e32 vcc, v5, v4
	s_nop 1
	v_cndmask_b32_e32 v3, v3, v10, vcc
	v_sub_u32_e32 v10, v5, v4
	v_cndmask_b32_e32 v5, v5, v10, vcc
	v_add_u32_e32 v10, 1, v3
	v_cmp_ge_u32_e32 vcc, v5, v4
	v_add_u32_e32 v5, 1, v11
	s_nop 0
	v_cndmask_b32_e32 v3, v3, v10, vcc
	v_mul_lo_u32 v10, v4, v3
	v_add_u32_e32 v4, v10, v4
	v_cmp_ne_u32_e32 vcc, v5, v4
	s_and_saveexec_b64 s[8:9], vcc
	s_xor_b64 s[8:9], exec, s[8:9]
	s_cbranch_execz .LBB0_734
	s_movk_i32 s26, 0xd00
	buffer_inv sc1
	s_lshl_b64 s[14:15], s[26:27], 2
	s_add_u32 s38, s6, s14
	s_addc_u32 s39, s7, s15
	s_waitcnt lgkmcnt(0)
	v_mad_u32_u24 v3, v3, v1, v1
	global_load_dword v1, v2, s[38:39] sc1
	s_waitcnt vmcnt(0)
	v_cmp_gt_u32_e32 vcc, v3, v1
	s_and_saveexec_b64 s[36:37], vcc
	s_cbranch_execz .LBB0_733
	s_mov_b32 s13, 1
	s_mov_b64 s[60:61], 0
	s_branch .LBB0_724

.LBB0_726:
	global_load_dword v1, v2, s[38:39] sc1
	s_add_i32 s13, s13, 1
	s_mov_b64 s[72:73], -1
	s_waitcnt vmcnt(0)
	v_cmp_le_u32_e32 vcc, v3, v1
	s_orn2_b64 s[70:71], vcc, exec
	s_branch .LBB0_723

.LBB0_737:
	s_or_b64 exec, exec, s[36:37]
	v_cvt_f32_u32_e32 v5, v1
	s_waitcnt vmcnt(0)
	v_readfirstlane_b32 s8, v4
	s_add_u32 s36, s6, 0x3400
	s_addc_u32 s37, s7, 0
	v_rcp_iflag_f32_e32 v5, v5
	v_add_u32_e32 v3, s8, v3
	v_add_u32_e32 v10, 1, v3
	s_mov_b64 s[38:39], -1
	v_mul_f32_e32 v4, 0x4f7ffffe, v5
	v_cvt_u32_f32_e32 v4, v4
	v_sub_u32_e32 v5, 0, v1
	v_mul_lo_u32 v5, v5, v4
	v_mul_hi_u32 v5, v4, v5
	v_add_u32_e32 v4, v4, v5
	v_mul_hi_u32 v4, v3, v4
	v_mul_lo_u32 v5, v4, v1
	v_sub_u32_e32 v3, v3, v5
	v_add_u32_e32 v11, 1, v4
	v_cmp_ge_u32_e32 vcc, v3, v1
	v_sub_u32_e32 v5, v3, v1
	s_nop 0
	v_cndmask_b32_e32 v4, v4, v11, vcc
	v_cndmask_b32_e32 v3, v3, v5, vcc
	v_add_u32_e32 v5, 1, v4
	v_cmp_ge_u32_e32 vcc, v3, v1
	s_nop 1
	v_cndmask_b32_e32 v3, v4, v5, vcc
	v_mul_lo_u32 v4, v1, v3
	v_add_u32_e32 v1, v4, v1
	v_cmp_ne_u32_e32 vcc, v10, v1
	v_mov_b32_e32 v3, v1
	v_mov_b64_e32 v[4:5], s[36:37]
	s_and_saveexec_b64 s[8:9], vcc
	s_cbranch_execz .LBB0_749
	global_load_dword v1, v2, s[36:37] sc1
	s_mov_b64 s[68:69], 0
	s_waitcnt vmcnt(0)
	v_cmp_gt_u32_e32 vcc, v3, v1
	s_and_saveexec_b64 s[60:61], vcc
	s_cbranch_execz .LBB0_748
	s_add_u32 s38, s6, 0x200
	s_addc_u32 s39, s7, 0
	s_mov_b32 s13, 1
	s_branch .LBB0_741

.LBB0_743:
	global_load_dword v1, v2, s[36:37] sc1
	s_add_i32 s13, s13, 1
	s_mov_b64 s[74:75], -1
	s_waitcnt vmcnt(0)
	v_cmp_le_u32_e32 vcc, v3, v1
	s_orn2_b64 s[72:73], vcc, exec
	s_branch .LBB0_740

.LBB0_749:
	s_or_b64 exec, exec, s[8:9]
	s_and_saveexec_b64 s[8:9], s[38:39]
	s_cbranch_execz .LBB0_751
.LBB0_751:
	s_or_b64 exec, exec, s[8:9]
	s_mov_b64 s[8:9], exec
	v_mbcnt_lo_u32_b32 v1, s8, 0
	v_mbcnt_hi_u32_b32 v1, s9, v1
	v_cmp_eq_u32_e32 vcc, 0, v1
	s_waitcnt vmcnt(0)
	s_and_saveexec_b64 s[36:37], vcc
	s_cbranch_execz .LBB0_753
	s_add_i32 s26, s12, 0x900
	s_lshl_b64 s[12:13], s[26:27], 2
	s_add_u32 s6, s6, s12
	s_addc_u32 s7, s7, s13
	s_bcnt1_i32_b64 s8, s[8:9]
	v_mov_b32_e32 v1, s8
	s_nop 0

.LBB0_775:
	s_or_b64 exec, exec, s[38:39]
	v_cvt_f32_u32_e32 v11, v5
	s_waitcnt vmcnt(0)
	v_readfirstlane_b32 s13, v10
	v_sub_u32_e32 v10, 0, v5
	v_rcp_iflag_f32_e32 v11, v11
	v_add_u32_e32 v12, s13, v3
	v_mul_f32_e32 v11, 0x4f7ffffe, v11
	v_cvt_u32_f32_e32 v11, v11
	v_mul_lo_u32 v3, v10, v11
	v_mul_hi_u32 v3, v11, v3
	v_add_u32_e32 v3, v11, v3
	v_mul_hi_u32 v3, v12, v3
	v_mul_lo_u32 v10, v3, v5
	v_sub_u32_e32 v10, v12, v10
	v_add_u32_e32 v11, 1, v3
	v_cmp_ge_u32_e32 vcc, v10, v5
	s_nop 1
	v_cndmask_b32_e32 v3, v3, v11, vcc
	v_sub_u32_e32 v11, v10, v5
	v_cndmask_b32_e32 v10, v10, v11, vcc
	v_add_u32_e32 v11, 1, v3
	v_cmp_ge_u32_e32 vcc, v10, v5
	v_add_u32_e32 v10, 1, v12
	s_nop 0
	v_cndmask_b32_e32 v3, v3, v11, vcc
	v_mul_lo_u32 v11, v5, v3
	v_add_u32_e32 v5, v11, v5
	v_cmp_ne_u32_e32 vcc, v10, v5
	s_and_saveexec_b64 s[14:15], vcc
	s_xor_b64 s[36:37], exec, s[14:15]
	s_cbranch_execz .LBB0_789
	s_movk_i32 s26, 0xd00
	buffer_inv sc1
	s_lshl_b64 s[14:15], s[26:27], 2
	s_add_u32 s74, s70, s14
	s_addc_u32 s75, s71, s15
	s_waitcnt lgkmcnt(0)
	v_mad_u32_u24 v3, v3, v4, v4
	global_load_dword v4, v2, s[74:75] sc1
	s_waitcnt vmcnt(0)
	v_cmp_gt_u32_e32 vcc, v3, v4
	s_and_saveexec_b64 s[38:39], vcc
	s_cbranch_execz .LBB0_788
	s_mov_b32 s13, 1
	s_mov_b64 s[76:77], 0
	s_branch .LBB0_779

.LBB0_781:
	global_load_dword v4, v2, s[74:75] sc1
	s_add_i32 s13, s13, 1
	s_mov_b64 s[82:83], -1
	s_waitcnt vmcnt(0)
	v_cmp_le_u32_e32 vcc, v3, v4
	s_orn2_b64 s[80:81], vcc, exec
	s_branch .LBB0_778

.LBB0_792:
	s_or_b64 exec, exec, s[38:39]
	s_waitcnt vmcnt(0)
	v_readfirstlane_b32 s13, v5
	v_sub_u32_e32 v10, 0, v4
	s_add_u32 s36, s70, 0x3400
	v_add_u32_e32 v5, s13, v3
	v_cvt_f32_u32_e32 v3, v4
	s_addc_u32 s37, s71, 0
	s_mov_b64 s[74:75], -1
	v_rcp_iflag_f32_e32 v3, v3
	s_nop 0
	v_mul_f32_e32 v3, 0x4f7ffffe, v3
	v_cvt_u32_f32_e32 v3, v3
	v_mul_lo_u32 v10, v10, v3
	v_mul_hi_u32 v10, v3, v10
	v_add_u32_e32 v3, v3, v10
	v_mul_hi_u32 v3, v5, v3
	v_mul_lo_u32 v10, v3, v4
	v_sub_u32_e32 v10, v5, v10
	v_cmp_ge_u32_e32 vcc, v10, v4
	v_add_u32_e32 v11, 1, v3
	v_add_u32_e32 v5, 1, v5
	v_cndmask_b32_e32 v3, v3, v11, vcc
	v_sub_u32_e32 v11, v10, v4
	v_cndmask_b32_e32 v10, v10, v11, vcc
	v_cmp_ge_u32_e32 vcc, v10, v4
	v_add_u32_e32 v10, 1, v3
	s_nop 0
	v_cndmask_b32_e32 v3, v3, v10, vcc
	v_mul_lo_u32 v10, v4, v3
	v_add_u32_e32 v4, v10, v4
	v_cmp_ne_u32_e32 vcc, v5, v4
	v_mov_b32_e32 v3, v4
	v_mov_b64_e32 v[4:5], s[36:37]
	s_and_saveexec_b64 s[38:39], vcc
	s_cbranch_execz .LBB0_804
	global_load_dword v4, v2, s[36:37] sc1
	s_mov_b64 s[78:79], 0
	s_waitcnt vmcnt(0)
	v_cmp_gt_u32_e32 vcc, v3, v4
	s_and_saveexec_b64 s[76:77], vcc
	s_cbranch_execz .LBB0_803
	s_add_u32 s74, s70, 0x200
	s_addc_u32 s75, s71, 0
	s_mov_b32 s13, 1
	s_branch .LBB0_796

.LBB0_798:
	global_load_dword v4, v2, s[36:37] sc1
	s_add_i32 s13, s13, 1
	s_mov_b64 s[84:85], -1
	s_waitcnt vmcnt(0)
	v_cmp_le_u32_e32 vcc, v3, v4
	s_orn2_b64 s[82:83], vcc, exec
	s_branch .LBB0_795

.LBB0_804:
	s_or_b64 exec, exec, s[38:39]
	s_and_saveexec_b64 s[36:37], s[74:75]
	s_cbranch_execz .LBB0_806
.LBB0_806:
	s_or_b64 exec, exec, s[36:37]
	s_mov_b64 s[36:37], exec
	v_mbcnt_lo_u32_b32 v3, s36, 0
	v_mbcnt_hi_u32_b32 v3, s37, v3
	v_cmp_eq_u32_e32 vcc, 0, v3
	s_waitcnt vmcnt(0)
	s_and_saveexec_b64 s[38:39], vcc
	s_cbranch_execz .LBB0_808
	s_add_i32 s26, s12, 0x900
	s_lshl_b64 s[12:13], s[26:27], 2
	s_add_u32 s12, s70, s12
	s_addc_u32 s13, s71, s13
	s_bcnt1_i32_b64 s14, s[36:37]
	v_mov_b32_e32 v3, s14
	s_nop 0

.LBB0_896:
	s_or_b64 exec, exec, s[8:9]
	v_cvt_f32_u32_e32 v10, v4
	s_waitcnt vmcnt(0)
	v_readfirstlane_b32 s6, v5
	v_sub_u32_e32 v5, 0, v4
	v_rcp_iflag_f32_e32 v10, v10
	v_add_u32_e32 v11, s6, v3
	v_mul_f32_e32 v10, 0x4f7ffffe, v10
	v_cvt_u32_f32_e32 v10, v10
	v_mul_lo_u32 v3, v5, v10
	v_mul_hi_u32 v3, v10, v3
	v_add_u32_e32 v3, v10, v3
	v_mul_hi_u32 v3, v11, v3
	v_mul_lo_u32 v5, v3, v4
	v_sub_u32_e32 v5, v11, v5
	v_add_u32_e32 v10, 1, v3
	v_cmp_ge_u32_e32 vcc, v5, v4
	s_nop 1
	v_cndmask_b32_e32 v3, v3, v10, vcc
	v_sub_u32_e32 v10, v5, v4
	v_cndmask_b32_e32 v5, v5, v10, vcc
	v_add_u32_e32 v10, 1, v3
	v_cmp_ge_u32_e32 vcc, v5, v4
	v_add_u32_e32 v5, 1, v11
	s_nop 0
	v_cndmask_b32_e32 v3, v3, v10, vcc
	v_mul_lo_u32 v10, v4, v3
	v_add_u32_e32 v4, v10, v4
	v_cmp_ne_u32_e32 vcc, v5, v4
	s_and_saveexec_b64 s[6:7], vcc
	s_xor_b64 s[6:7], exec, s[6:7]
	s_cbranch_execz .LBB0_910
	s_movk_i32 s26, 0xd00
	buffer_inv sc1
	s_lshl_b64 s[8:9], s[26:27], 2
	s_add_u32 s10, s4, s8
	s_addc_u32 s11, s5, s9
	s_waitcnt lgkmcnt(0)
	v_mad_u32_u24 v3, v3, v1, v1
	global_load_dword v1, v2, s[10:11] sc1
	s_waitcnt vmcnt(0)
	v_cmp_gt_u32_e32 vcc, v3, v1
	s_and_saveexec_b64 s[8:9], vcc
	s_cbranch_execz .LBB0_909
	s_mov_b32 s13, 1
	s_mov_b64 s[36:37], 0
	s_branch .LBB0_900

.LBB0_902:
	global_load_dword v1, v2, s[10:11] sc1
	s_add_i32 s13, s13, 1
	s_mov_b64 s[62:63], -1
	s_waitcnt vmcnt(0)
	v_cmp_le_u32_e32 vcc, v3, v1
	s_orn2_b64 s[58:59], vcc, exec
	s_branch .LBB0_899

.LBB0_913:
	s_or_b64 exec, exec, s[8:9]
	v_cvt_f32_u32_e32 v5, v1
	s_waitcnt vmcnt(0)
	v_readfirstlane_b32 s6, v4
	s_add_u32 s8, s4, 0x3400
	s_addc_u32 s9, s5, 0
	v_rcp_iflag_f32_e32 v5, v5
	v_add_u32_e32 v3, s6, v3
	v_add_u32_e32 v10, 1, v3
	s_mov_b64 s[10:11], -1
	v_mul_f32_e32 v4, 0x4f7ffffe, v5
	v_cvt_u32_f32_e32 v4, v4
	v_sub_u32_e32 v5, 0, v1
	v_mul_lo_u32 v5, v5, v4
	v_mul_hi_u32 v5, v4, v5
	v_add_u32_e32 v4, v4, v5
	v_mul_hi_u32 v4, v3, v4
	v_mul_lo_u32 v5, v4, v1
	v_sub_u32_e32 v3, v3, v5
	v_add_u32_e32 v11, 1, v4
	v_cmp_ge_u32_e32 vcc, v3, v1
	v_sub_u32_e32 v5, v3, v1
	s_nop 0
	v_cndmask_b32_e32 v4, v4, v11, vcc
	v_cndmask_b32_e32 v3, v3, v5, vcc
	v_add_u32_e32 v5, 1, v4
	v_cmp_ge_u32_e32 vcc, v3, v1
	s_nop 1
	v_cndmask_b32_e32 v3, v4, v5, vcc
	v_mul_lo_u32 v4, v1, v3
	v_add_u32_e32 v1, v4, v1
	v_cmp_ne_u32_e32 vcc, v10, v1
	v_mov_b32_e32 v3, v1
	v_mov_b64_e32 v[4:5], s[8:9]
	s_and_saveexec_b64 s[6:7], vcc
	s_cbranch_execz .LBB0_925
	global_load_dword v1, v2, s[8:9] sc1
	s_mov_b64 s[38:39], 0
	s_waitcnt vmcnt(0)
	v_cmp_gt_u32_e32 vcc, v3, v1
	s_and_saveexec_b64 s[36:37], vcc
	s_cbranch_execz .LBB0_924
	s_add_u32 s10, s4, 0x200
	s_addc_u32 s11, s5, 0
	s_mov_b32 s13, 1
	s_branch .LBB0_917

.LBB0_919:
	global_load_dword v1, v2, s[8:9] sc1
	s_add_i32 s13, s13, 1
	s_mov_b64 s[64:65], -1
	s_waitcnt vmcnt(0)
	v_cmp_le_u32_e32 vcc, v3, v1
	s_orn2_b64 s[62:63], vcc, exec
	s_branch .LBB0_916

.LBB0_925:
	s_or_b64 exec, exec, s[6:7]
	s_and_saveexec_b64 s[6:7], s[10:11]
	s_cbranch_execz .LBB0_927
.LBB0_927:
	s_or_b64 exec, exec, s[6:7]
	s_mov_b64 s[6:7], exec
	v_mbcnt_lo_u32_b32 v1, s6, 0
	v_mbcnt_hi_u32_b32 v1, s7, v1
	v_cmp_eq_u32_e32 vcc, 0, v1
	s_waitcnt vmcnt(0)
	s_and_saveexec_b64 s[8:9], vcc
	s_cbranch_execz .LBB0_518
	s_add_i32 s26, s12, 0x900
	s_lshl_b64 s[10:11], s[26:27], 2
	s_add_u32 s4, s4, s10
	s_addc_u32 s5, s5, s11
	s_bcnt1_i32_b64 s6, s[6:7]
	v_mov_b32_e32 v1, s6
	s_nop 0
	s_branch .LBB0_518

.LBB0_972:
	s_or_b64 exec, exec, s[6:7]
	s_cmp_gt_u32 s14, 63
	s_cbranch_scc1 .LBB0_982
	buffer_inv sc1
	s_memrealtime s[6:7]
	s_lshl_b32 s8, s18, 6
	s_ashr_i32 s9, s8, 31
	s_lshl_b64 s[8:9], s[8:9], 2
	s_add_u32 s8, s10, s8
	s_addc_u32 s9, s11, s9
	v_mov_b32_e32 v5, 0
	s_waitcnt lgkmcnt(0)
	v_mov_b64_e32 v[2:3], 0x1e8481
	s_branch .LBB0_976

.LBB0_979:
	s_and_saveexec_b64 s[6:7], s[2:3]
	s_add_i32 s2, 0, 0x21400
	v_cndmask_b32_e64 v2, 0, 1, s[10:11]
	v_mov_b32_e32 v3, s2
	ds_write_b32 v3, v2
	s_or_b64 exec, exec, s[6:7]
